# v109 plus DPP row rotations in the finalize-C row loop
# speedup vs baseline: 1.0004x; 1.0004x over previous
; __device__ __forceinline__ float bf2f(bfu h) { return __uint_as_float(((unsigned)h) << 16); }
; __device__ __forceinline__ unsigned pack2(float a, float b) { return (unsigned)f2bf(a) | ((unsigned)f2bf(b) << 16); }
; __device__ __forceinline__ float frsq(float x) { return __builtin_amdgcn_rsqf(x); }
; __device__ __forceinline__ float sigmoidf_(float x) { return frcp(1.0f + fexp(-x)); }
; #define SHX(v, m) shx_((v), (m), lane)
; __device__ void cd_fin_rows(const Params& p, int L, int row0, int nrows, const bool doC, const bool doD) {
;     ...
;     if (doC) {
;     bf16x8 o = *(const bf16x8*)(pr + 3584 + c0);
;     bf16x8 hg = *(const bf16x8*)(pr + 1536 + 1536 + c0);
;     float of[8]; float ss = 0.f;
;     for (int e = 0; e < 8; ++e) { of[e] = bf2f((bfu)o[e]); ss += of[e] * of[e]; }
;     ss += SHX(ss, 1); ss += SHX(ss, 2); ss += SHX(ss, 4); ss += SHX(ss, 8);
;     const float rs = frsq(ss * (1.0f / 128.0f) + 1e-6f);
;     float ra[8];
;     for (int e = 0; e < 8; ++e) ra[e] = of[e] * rs * p.hg_norm_g[li * 128 + ((c0 + e) & 127)] * sigmoidf_(bf2f((bfu)hg[e]));
;     uint4 wa; wa.x = pack2(ra[0], ra[1]); wa.y = pack2(ra[2], ra[3]); wa.z = pack2(ra[4], ra[5]); wa.w = pack2(ra[6], ra[7]);
;     *(uint4*)(pr + 1536 + c0) = wa;
;     }
.LBB0_33:
	global_load_dwordx4 v[10:13], v[4:5], off offset:-1024
	global_load_dwordx4 v[14:17], v[4:5], off
	global_load_dwordx4 v[18:21], v[2:3], off
	global_load_dwordx4 v[22:25], v[2:3], off offset:16
	v_add_u32_e32 v0, 8, v0
	v_cmp_lt_i32_e32 vcc, s21, v0
	s_or_b64 s[14:15], vcc, s[14:15]
	s_waitcnt vmcnt(0)
	v_lshlrev_b32_e32 v28, 16, v10
	v_and_b32_e32 v29, 0xffff0000, v10
	v_lshlrev_b32_e32 v30, 16, v11
	v_and_b32_e32 v31, 0xffff0000, v11
	v_lshlrev_b32_e32 v32, 16, v12
	v_and_b32_e32 v33, 0xffff0000, v12
	v_lshlrev_b32_e32 v34, 16, v13
	v_and_b32_e32 v35, 0xffff0000, v13
	s_waitcnt vmcnt(2)
	v_lshlrev_b32_e32 v11, 16, v15
	v_lshlrev_b32_e32 v10, 16, v14
	v_and_b32_e32 v13, 0xffff0000, v15
	v_and_b32_e32 v12, 0xffff0000, v14
	s_waitcnt vmcnt(0)
	v_mov_b32_e32 v26, v22
	v_mov_b32_e32 v27, v24
	v_mov_b32_e32 v24, v23
	v_mul_f32_e32 v36, 0xbfb8aa3b, v28
	v_mul_f32_e32 v37, 0xbfb8aa3b, v29
	v_pk_mul_f32 v[22:23], v[10:11], v[10:11]
	v_pk_mul_f32 v[28:29], v[12:13], v[12:13]
	v_mov_b32_e32 v14, v18
	v_lshlrev_b32_e32 v18, 16, v16
	v_and_b32_e32 v16, 0xffff0000, v16
	v_add_f32_e32 v22, v22, v28
	v_mul_f32_e32 v38, 0xbfb8aa3b, v30
	v_mul_f32_e32 v39, 0xbfb8aa3b, v31
	v_mov_b32_e32 v30, v16
	v_mov_b32_e32 v31, v18
	v_add_f32_e32 v22, v23, v22
	v_mov_b32_e32 v15, v20
	v_mov_b32_e32 v20, v19
	v_lshlrev_b32_e32 v19, 16, v17
	v_and_b32_e32 v17, 0xffff0000, v17
	v_pk_mul_f32 v[30:31], v[30:31], v[30:31]
	v_add_f32_e32 v22, v29, v22
	v_mul_f32_e32 v40, 0xbfb8aa3b, v32
	v_mul_f32_e32 v41, 0xbfb8aa3b, v33
	v_mov_b32_e32 v32, v17
	v_mov_b32_e32 v33, v19
	v_add_f32_e32 v22, v31, v22
	v_pk_mul_f32 v[32:33], v[32:33], v[32:33]
	v_add_f32_e32 v22, v30, v22
	v_add_f32_e32 v22, v33, v22
	v_add_f32_e32 v22, v32, v22
	v_exp_f32_e32 v36, v36
	v_exp_f32_e32 v37, v37
	v_mul_f32_e32 v35, 0xbfb8aa3b, v35
	v_exp_f32_e32 v28, v41
	s_waitcnt lgkmcnt(0)
	s_nop 1
	v_add_f32_dpp v22, v22, v22 row_ror:1 row_mask:0xf bank_mask:0xf
	v_add_f32_e32 v31, 1.0, v36
	v_mul_f32_e32 v34, 0xbfb8aa3b, v34
	v_exp_f32_e32 v39, v39
	v_exp_f32_e32 v40, v40
	s_waitcnt lgkmcnt(0)
	s_nop 1
	v_add_f32_dpp v23, v22, v22 row_ror:2 row_mask:0xf bank_mask:0xf
	v_rcp_f32_e32 v22, v31
	v_exp_f32_e32 v30, v35
	v_exp_f32_e32 v38, v38
	v_exp_f32_e32 v29, v34
	s_waitcnt lgkmcnt(0)
	s_nop 1
	v_add_f32_dpp v31, v23, v23 row_ror:4 row_mask:0xf bank_mask:0xf
	v_add_f32_e32 v32, 1.0, v37
	v_add_f32_e32 v37, 1.0, v28
	v_rcp_f32_e32 v28, v32
	v_add_f32_e32 v34, 1.0, v39
	s_waitcnt lgkmcnt(0)
	s_nop 1
	v_add_f32_dpp v31, v31, v31 row_ror:8 row_mask:0xf bank_mask:0xf
	v_fmamk_f32 v31, v31, 0x3c000000, v201
	v_rsq_f32_e32 v32, v31
	v_add_f32_e32 v35, 1.0, v40
	v_add_f32_e32 v39, 1.0, v30
	v_add_f32_e32 v33, 1.0, v38
	v_add_f32_e32 v38, 1.0, v29
	v_rcp_f32_e32 v29, v34
	v_rcp_f32_e32 v30, v35
	v_rcp_f32_e32 v34, v37
	v_rcp_f32_e32 v35, v39
	v_rcp_f32_e32 v23, v33
	v_rcp_f32_e32 v31, v38
	v_pk_mul_f32 v[12:13], v[32:33], v[12:13] op_sel_hi:[0,1]
	v_pk_mul_f32 v[16:17], v[32:33], v[16:17] op_sel_hi:[0,1]
	v_pk_mul_f32 v[10:11], v[32:33], v[10:11] op_sel_hi:[0,1]
	v_pk_mul_f32 v[18:19], v[32:33], v[18:19] op_sel_hi:[0,1]
	v_pk_mul_f32 v[12:13], v[20:21], v[12:13]
	v_pk_mul_f32 v[16:17], v[24:25], v[16:17]
	v_pk_mul_f32 v[10:11], v[14:15], v[10:11]
	v_pk_mul_f32 v[14:15], v[26:27], v[18:19]
	v_pk_mul_f32 v[12:13], v[28:29], v[12:13]
	v_pk_mul_f32 v[16:17], v[34:35], v[16:17]
	v_pk_mul_f32 v[10:11], v[22:23], v[10:11]
	v_pk_mul_f32 v[14:15], v[30:31], v[14:15]
	v_and_b32_sdwa v20, v13, v220 dst_sel:DWORD dst_unused:UNUSED_PAD src0_sel:WORD_1 src1_sel:DWORD
	v_and_b32_sdwa v21, v12, v220 dst_sel:DWORD dst_unused:UNUSED_PAD src0_sel:WORD_1 src1_sel:DWORD
	v_and_b32_sdwa v24, v17, v220 dst_sel:DWORD dst_unused:UNUSED_PAD src0_sel:WORD_1 src1_sel:DWORD
	v_and_b32_sdwa v25, v16, v220 dst_sel:DWORD dst_unused:UNUSED_PAD src0_sel:WORD_1 src1_sel:DWORD
	v_and_b32_sdwa v18, v11, v220 dst_sel:DWORD dst_unused:UNUSED_PAD src0_sel:WORD_1 src1_sel:DWORD
	v_and_b32_sdwa v19, v10, v220 dst_sel:DWORD dst_unused:UNUSED_PAD src0_sel:WORD_1 src1_sel:DWORD
	v_and_b32_sdwa v22, v15, v220 dst_sel:DWORD dst_unused:UNUSED_PAD src0_sel:WORD_1 src1_sel:DWORD
	v_and_b32_sdwa v23, v14, v220 dst_sel:DWORD dst_unused:UNUSED_PAD src0_sel:WORD_1 src1_sel:DWORD
	v_add3_u32 v13, v13, v20, s72
	v_add3_u32 v12, v12, v21, s72
	v_add3_u32 v17, v17, v24, s72
	v_add3_u32 v16, v16, v25, s72
	v_add3_u32 v10, v10, v19, s72
	v_add3_u32 v11, v11, v18, s72
	v_add3_u32 v14, v14, v23, s72
	v_add3_u32 v15, v15, v22, s72
	v_and_b32_e32 v13, 0xffff0000, v13
	v_and_b32_e32 v12, 0xffff0000, v12
	v_and_b32_e32 v17, 0xffff0000, v17
	v_and_b32_e32 v16, 0xffff0000, v16
	v_or_b32_sdwa v11, v13, v11 dst_sel:DWORD dst_unused:UNUSED_PAD src0_sel:DWORD src1_sel:WORD_1
	v_or_b32_sdwa v10, v12, v10 dst_sel:DWORD dst_unused:UNUSED_PAD src0_sel:DWORD src1_sel:WORD_1
	v_or_b32_sdwa v13, v17, v15 dst_sel:DWORD dst_unused:UNUSED_PAD src0_sel:DWORD src1_sel:WORD_1
	v_or_b32_sdwa v12, v16, v14 dst_sel:DWORD dst_unused:UNUSED_PAD src0_sel:DWORD src1_sel:WORD_1
	global_store_dwordx4 v[4:5], v[10:13], off offset:-4096
	v_lshl_add_u64 v[4:5], v[4:5], 0, s[26:27]
	s_andn2_b64 exec, exec, s[14:15]
	s_cbranch_execnz .LBB0_33
	s_branch .LBB0_30
